# stack16: stack10 + cache policy: f32 d_out-only tensors (dk/dv copies, final y) stored write-through sc1 so they do not occupy the XCD L2
# speedup vs baseline: 1.0095x; 1.0018x over previous
.LBB0_317:
	v_pk_mul_f32 v[242:243], v[206:207], v[176:177] op_sel_hi:[1,0]
	v_pk_mul_f32 v[246:247], v[210:211], v[176:177] op_sel_hi:[1,0]
	v_ashrrev_i32_e32 v203, 31, v202
	s_waitcnt vmcnt(3)
	v_pk_mul_f32 v[244:245], v[142:143], v[242:243]
	v_pk_mul_f32 v[242:243], v[140:141], v[246:247]
	v_lshl_add_u64 v[246:247], v[202:203], 2, v[220:221]
	global_store_dwordx4 v[246:247], v[242:245], off sc1
	v_cvt_pk_bf16_f32 v220, v242, v243
	v_cvt_pk_bf16_f32 v221, v244, v245
	v_lshl_add_u64 v[242:243], v[202:203], 1, v[222:223]
	global_store_dwordx2 v[242:243], v[220:221], off
	v_pk_mul_f32 v[220:221], v[204:205], v[176:177] op_sel_hi:[1,0]
	v_pk_mul_f32 v[244:245], v[208:209], v[176:177] op_sel_hi:[1,0]
	s_waitcnt vmcnt(4)
	v_pk_mul_f32 v[222:223], v[138:139], v[220:221]
	v_pk_mul_f32 v[220:221], v[136:137], v[244:245]
	global_store_dwordx4 v[246:247], v[220:223], off offset:64 sc1
	v_pk_mul_f32 v[244:245], v[214:215], v[176:177] op_sel_hi:[1,0]
	s_mov_b64 s[44:45], 0
	v_cvt_pk_bf16_f32 v220, v220, v221
	v_cvt_pk_bf16_f32 v221, v222, v223
	global_store_dwordx2 v[242:243], v[220:221], off offset:32
	v_pk_mul_f32 v[220:221], v[212:213], v[176:177] op_sel_hi:[1,0]
	s_waitcnt vmcnt(5)
	v_pk_mul_f32 v[222:223], v[134:135], v[220:221]
	v_pk_mul_f32 v[220:221], v[132:133], v[244:245]
	global_store_dwordx4 v[246:247], v[220:223], off offset:128 sc1
	v_pk_mul_f32 v[244:245], v[218:219], v[176:177] op_sel_hi:[1,0]
	s_nop 0
	v_cvt_pk_bf16_f32 v220, v220, v221
	v_cvt_pk_bf16_f32 v221, v222, v223
	global_store_dwordx2 v[242:243], v[220:221], off offset:64
	v_pk_mul_f32 v[220:221], v[216:217], v[176:177] op_sel_hi:[1,0]
	s_waitcnt vmcnt(6)
	v_pk_mul_f32 v[222:223], v[130:131], v[220:221]
	v_pk_mul_f32 v[220:221], v[128:129], v[244:245]
	global_store_dwordx4 v[246:247], v[220:223], off offset:192 sc1
	s_nop 1
	v_cvt_pk_bf16_f32 v220, v220, v221
	v_cvt_pk_bf16_f32 v221, v222, v223
	global_store_dwordx2 v[242:243], v[220:221], off offset:96

.LBB0_325:
	v_pk_mul_f32 v[242:243], v[206:207], v[176:177] op_sel_hi:[1,0]
	v_pk_mul_f32 v[246:247], v[210:211], v[176:177] op_sel_hi:[1,0]
	v_ashrrev_i32_e32 v203, 31, v202
	s_waitcnt vmcnt(3)
	v_pk_mul_f32 v[244:245], v[142:143], v[242:243]
	v_pk_mul_f32 v[242:243], v[140:141], v[246:247]
	v_lshl_add_u64 v[246:247], v[202:203], 2, v[220:221]
	global_store_dwordx4 v[246:247], v[242:245], off sc1
	v_cvt_pk_bf16_f32 v220, v242, v243
	v_cvt_pk_bf16_f32 v221, v244, v245
	v_lshl_add_u64 v[242:243], v[202:203], 1, v[222:223]
	global_store_dwordx2 v[242:243], v[220:221], off
	v_pk_mul_f32 v[220:221], v[204:205], v[176:177] op_sel_hi:[1,0]
	v_pk_mul_f32 v[244:245], v[208:209], v[176:177] op_sel_hi:[1,0]
	s_waitcnt vmcnt(4)
	v_pk_mul_f32 v[222:223], v[138:139], v[220:221]
	v_pk_mul_f32 v[220:221], v[136:137], v[244:245]
	global_store_dwordx4 v[246:247], v[220:223], off offset:64 sc1
	v_pk_mul_f32 v[244:245], v[214:215], v[176:177] op_sel_hi:[1,0]
	s_mov_b64 s[46:47], 0
	v_cvt_pk_bf16_f32 v220, v220, v221
	v_cvt_pk_bf16_f32 v221, v222, v223
	global_store_dwordx2 v[242:243], v[220:221], off offset:32
	v_pk_mul_f32 v[220:221], v[212:213], v[176:177] op_sel_hi:[1,0]
	s_waitcnt vmcnt(5)
	v_pk_mul_f32 v[222:223], v[134:135], v[220:221]
	v_pk_mul_f32 v[220:221], v[132:133], v[244:245]
	global_store_dwordx4 v[246:247], v[220:223], off offset:128 sc1
	v_pk_mul_f32 v[244:245], v[218:219], v[176:177] op_sel_hi:[1,0]
	s_nop 0
	v_cvt_pk_bf16_f32 v220, v220, v221
	v_cvt_pk_bf16_f32 v221, v222, v223
	global_store_dwordx2 v[242:243], v[220:221], off offset:64
	v_pk_mul_f32 v[220:221], v[216:217], v[176:177] op_sel_hi:[1,0]
	s_waitcnt vmcnt(6)
	v_pk_mul_f32 v[222:223], v[130:131], v[220:221]
	v_pk_mul_f32 v[220:221], v[128:129], v[244:245]
	global_store_dwordx4 v[246:247], v[220:223], off offset:192 sc1
	s_nop 1
	v_cvt_pk_bf16_f32 v220, v220, v221
	v_cvt_pk_bf16_f32 v221, v222, v223
	global_store_dwordx2 v[242:243], v[220:221], off offset:96

.LBB0_373:
	v_pk_mul_f32 v[242:243], v[206:207], v[176:177] op_sel_hi:[1,0]
	v_pk_mul_f32 v[246:247], v[210:211], v[176:177] op_sel_hi:[1,0]
	s_waitcnt vmcnt(3)
	v_pk_mul_f32 v[244:245], v[142:143], v[242:243]
	v_pk_mul_f32 v[242:243], v[140:141], v[246:247]
	v_ashrrev_i32_e32 v203, 31, v202
	v_lshl_add_u64 v[246:247], v[202:203], 2, v[220:221]
	v_cvt_pk_bf16_f32 v220, v242, v243
	v_cvt_pk_bf16_f32 v221, v244, v245
	v_lshl_add_u64 v[202:203], v[202:203], 1, v[222:223]
	global_store_dwordx4 v[246:247], v[242:245], off sc1
	global_store_dwordx2 v[202:203], v[220:221], off
	v_pk_mul_f32 v[220:221], v[204:205], v[176:177] op_sel_hi:[1,0]
	v_pk_mul_f32 v[242:243], v[208:209], v[176:177] op_sel_hi:[1,0]
	s_waitcnt vmcnt(4)
	v_pk_mul_f32 v[222:223], v[138:139], v[220:221]
	v_pk_mul_f32 v[220:221], v[136:137], v[242:243]
	global_store_dwordx4 v[246:247], v[220:223], off offset:64 sc1
	v_pk_mul_f32 v[242:243], v[214:215], v[176:177] op_sel_hi:[1,0]
	s_mov_b64 s[44:45], 0
	v_cvt_pk_bf16_f32 v220, v220, v221
	v_cvt_pk_bf16_f32 v221, v222, v223
	global_store_dwordx2 v[202:203], v[220:221], off offset:32
	v_pk_mul_f32 v[220:221], v[212:213], v[176:177] op_sel_hi:[1,0]
	s_waitcnt vmcnt(5)
	v_pk_mul_f32 v[222:223], v[134:135], v[220:221]
	v_pk_mul_f32 v[220:221], v[132:133], v[242:243]
	global_store_dwordx4 v[246:247], v[220:223], off offset:128 sc1
	v_pk_mul_f32 v[242:243], v[218:219], v[176:177] op_sel_hi:[1,0]
	s_nop 0
	v_cvt_pk_bf16_f32 v220, v220, v221
	v_cvt_pk_bf16_f32 v221, v222, v223
	global_store_dwordx2 v[202:203], v[220:221], off offset:64
	v_pk_mul_f32 v[220:221], v[216:217], v[176:177] op_sel_hi:[1,0]
	s_waitcnt vmcnt(6)
	v_pk_mul_f32 v[222:223], v[130:131], v[220:221]
	v_pk_mul_f32 v[220:221], v[128:129], v[242:243]
	global_store_dwordx4 v[246:247], v[220:223], off offset:192 sc1
	s_nop 1
	v_cvt_pk_bf16_f32 v220, v220, v221
	v_cvt_pk_bf16_f32 v221, v222, v223
	global_store_dwordx2 v[202:203], v[220:221], off offset:96

.Ltr_k2:
	s_cmp_lg_u64 s[42:43], 0
	s_mov_b32 s38, 0x1a788000
	s_cselect_b32 s38, s38, 0x18788000
	s_movk_i32 s39, 0x1000
	s_cselect_b32 s39, 0x2080, s39
	s_cselect_b32 s100, 0x2000, 0
	s_add_u32 s44, s96, s38
	s_addc_u32 s45, s97, 0
	s_lshl_b32 s101, s28, 9
	s_add_i32 s101, s101, s31
	s_mul_i32 s101, s101, s39
	s_add_i32 s101, s101, s100
	s_lshl_b32 s38, s29, 1
	s_add_i32 s101, s101, s38
	s_add_i32 s28, s28, s23
	s_add_i32 s29, s29, s35
	s_lshl_b32 s38, s28, 9
	s_add_i32 s38, s38, s31
	s_mul_i32 s38, s38, s39
	s_add_i32 s38, s38, s100
	s_lshl_b32 s28, s29, 1
	s_add_i32 s38, s38, s28
	s_lshl_b32 s100, s39, 7
	v_lshrrev_b32_e32 v244, 6, v224
	v_mul_u32_u24_e32 v244, 2560, v244
	v_add_u32_e32 v244, 0x20000, v244
	v_mul_u32_u24_e32 v208, 320, v239
	v_lshl_add_u32 v208, v238, 1, v208
	v_add_u32_e32 v208, v208, v244
	v_and_b32_e32 v210, 63, v229
	v_lshrrev_b32_e32 v211, 2, v210
	v_and_b32_e32 v210, 3, v210
	v_mul_u32_u24_e32 v209, 80, v211
	v_lshl_add_u32 v209, v210, 4, v209
	v_add_u32_e32 v209, v209, v244
	v_mul_lo_u32 v211, v211, s39
	v_lshl_add_u32 v210, v210, 4, v211
	s_lshl_b32 s28, s39, 4
	v_add_u32_e32 v211, s28, v210
	v_subrev_u32_e32 v220, s86, v196
	v_lshlrev_b32_e32 v220, 11, v220
	s_and_b32 s28, s74, 1
	s_lshl_b32 s28, s28, 8
	v_add_u32_e32 v244, s28, v198
	v_lshl_add_u32 v220, v244, 2, v220
	v_pk_mul_f32 v[128:129], v[124:125], v[194:195] op_sel_hi:[1,0]
	v_pk_mul_f32 v[130:131], v[126:127], v[194:195] op_sel_hi:[1,0]
	global_store_dwordx4 v220, v[128:131], s[48:49] sc1
	v_cvt_pk_bf16_f32 v132, v128, v129
	v_cvt_pk_bf16_f32 v133, v130, v131
	ds_write_b16 v208, v132
	ds_write_b16_d16_hi v208, v132 offset:80
	ds_write_b16 v208, v133 offset:160
	ds_write_b16_d16_hi v208, v133 offset:240
	v_pk_mul_f32 v[128:129], v[120:121], v[194:195] op_sel_hi:[1,0]
	v_pk_mul_f32 v[130:131], v[122:123], v[194:195] op_sel_hi:[1,0]
	global_store_dwordx4 v220, v[128:131], s[48:49] offset:64 sc1
	v_cvt_pk_bf16_f32 v132, v128, v129
	v_cvt_pk_bf16_f32 v133, v130, v131
	ds_write_b16 v208, v132 offset:1280
	ds_write_b16_d16_hi v208, v132 offset:1360
	ds_write_b16 v208, v133 offset:1440
	ds_write_b16_d16_hi v208, v133 offset:1520
	v_pk_mul_f32 v[128:129], v[108:109], v[190:191] op_sel_hi:[1,0]
	v_pk_mul_f32 v[130:131], v[110:111], v[190:191] op_sel_hi:[1,0]
	v_add_u32_e32 v244, 0x8000, v220
	global_store_dwordx4 v244, v[128:131], s[48:49] sc1
	v_cvt_pk_bf16_f32 v132, v128, v129
	v_cvt_pk_bf16_f32 v133, v130, v131
	ds_write_b16 v208, v132 offset:32
	ds_write_b16_d16_hi v208, v132 offset:112
	ds_write_b16 v208, v133 offset:192
	ds_write_b16_d16_hi v208, v133 offset:272
	v_pk_mul_f32 v[128:129], v[104:105], v[190:191] op_sel_hi:[1,0]
	v_pk_mul_f32 v[130:131], v[106:107], v[190:191] op_sel_hi:[1,0]
	v_add_u32_e32 v244, 0x8000, v220
	global_store_dwordx4 v244, v[128:131], s[48:49] offset:64 sc1
	v_cvt_pk_bf16_f32 v132, v128, v129
	v_cvt_pk_bf16_f32 v133, v130, v131
	ds_write_b16 v208, v132 offset:1312
	ds_write_b16_d16_hi v208, v132 offset:1392
	ds_write_b16 v208, v133 offset:1472
	ds_write_b16_d16_hi v208, v133 offset:1552
	s_waitcnt lgkmcnt(0)
	ds_read_b128 v[212:215], v209
	ds_read_b128 v[216:219], v209 offset:1280
	s_add_u32 s46, s44, s101
	s_addc_u32 s47, s45, 0
	s_waitcnt lgkmcnt(0)
	global_store_dwordx4 v210, v[212:215], s[46:47]
	global_store_dwordx4 v211, v[216:219], s[46:47]
	v_pk_mul_f32 v[128:129], v[92:93], v[172:173] op_sel_hi:[1,0]
	v_pk_mul_f32 v[130:131], v[94:95], v[172:173] op_sel_hi:[1,0]
	v_add_u32_e32 v244, 0x10000, v220
	global_store_dwordx4 v244, v[128:131], s[48:49] sc1
	v_cvt_pk_bf16_f32 v132, v128, v129
	v_cvt_pk_bf16_f32 v133, v130, v131
	ds_write_b16 v208, v132
	ds_write_b16_d16_hi v208, v132 offset:80
	ds_write_b16 v208, v133 offset:160
	ds_write_b16_d16_hi v208, v133 offset:240
	v_pk_mul_f32 v[128:129], v[88:89], v[172:173] op_sel_hi:[1,0]
	v_pk_mul_f32 v[130:131], v[90:91], v[172:173] op_sel_hi:[1,0]
	v_add_u32_e32 v244, 0x10000, v220
	global_store_dwordx4 v244, v[128:131], s[48:49] offset:64 sc1
	v_cvt_pk_bf16_f32 v132, v128, v129
	v_cvt_pk_bf16_f32 v133, v130, v131
	ds_write_b16 v208, v132 offset:1280
	ds_write_b16_d16_hi v208, v132 offset:1360
	ds_write_b16 v208, v133 offset:1440
	ds_write_b16_d16_hi v208, v133 offset:1520
	v_pk_mul_f32 v[128:129], v[76:77], v[168:169] op_sel_hi:[1,0]
	v_pk_mul_f32 v[130:131], v[78:79], v[168:169] op_sel_hi:[1,0]
	v_add_u32_e32 v244, 0x18000, v220
	global_store_dwordx4 v244, v[128:131], s[48:49] sc1
	v_cvt_pk_bf16_f32 v132, v128, v129
	v_cvt_pk_bf16_f32 v133, v130, v131
	ds_write_b16 v208, v132 offset:32
	ds_write_b16_d16_hi v208, v132 offset:112
	ds_write_b16 v208, v133 offset:192
	ds_write_b16_d16_hi v208, v133 offset:272
	v_pk_mul_f32 v[128:129], v[72:73], v[168:169] op_sel_hi:[1,0]
	v_pk_mul_f32 v[130:131], v[74:75], v[168:169] op_sel_hi:[1,0]
	v_add_u32_e32 v244, 0x18000, v220
	global_store_dwordx4 v244, v[128:131], s[48:49] offset:64 sc1
	v_cvt_pk_bf16_f32 v132, v128, v129
	v_cvt_pk_bf16_f32 v133, v130, v131
	ds_write_b16 v208, v132 offset:1312
	ds_write_b16_d16_hi v208, v132 offset:1392
	ds_write_b16 v208, v133 offset:1472
	ds_write_b16_d16_hi v208, v133 offset:1552
	s_waitcnt lgkmcnt(0)
	ds_read_b128 v[212:215], v209
	ds_read_b128 v[216:219], v209 offset:1280
	s_add_u32 s46, s44, s101
	s_addc_u32 s47, s45, 0
	s_waitcnt lgkmcnt(0)
	global_store_dwordx4 v210, v[212:215], s[46:47] offset:64
	global_store_dwordx4 v211, v[216:219], s[46:47] offset:64
	v_pk_mul_f32 v[128:129], v[116:117], v[194:195] op_sel_hi:[1,0]
	v_pk_mul_f32 v[130:131], v[118:119], v[194:195] op_sel_hi:[1,0]
	global_store_dwordx4 v220, v[128:131], s[48:49] offset:512 sc1
	v_cvt_pk_bf16_f32 v132, v128, v129
	v_cvt_pk_bf16_f32 v133, v130, v131
	ds_write_b16 v208, v132
	ds_write_b16_d16_hi v208, v132 offset:80
	ds_write_b16 v208, v133 offset:160
	ds_write_b16_d16_hi v208, v133 offset:240
	v_pk_mul_f32 v[128:129], v[112:113], v[194:195] op_sel_hi:[1,0]
	v_pk_mul_f32 v[130:131], v[114:115], v[194:195] op_sel_hi:[1,0]
	global_store_dwordx4 v220, v[128:131], s[48:49] offset:576 sc1
	v_cvt_pk_bf16_f32 v132, v128, v129
	v_cvt_pk_bf16_f32 v133, v130, v131
	ds_write_b16 v208, v132 offset:1280
	ds_write_b16_d16_hi v208, v132 offset:1360
	ds_write_b16 v208, v133 offset:1440
	ds_write_b16_d16_hi v208, v133 offset:1520
	v_pk_mul_f32 v[128:129], v[100:101], v[190:191] op_sel_hi:[1,0]
	v_pk_mul_f32 v[130:131], v[102:103], v[190:191] op_sel_hi:[1,0]
	v_add_u32_e32 v244, 0x8000, v220
	global_store_dwordx4 v244, v[128:131], s[48:49] offset:512 sc1
	v_cvt_pk_bf16_f32 v132, v128, v129
	v_cvt_pk_bf16_f32 v133, v130, v131
	ds_write_b16 v208, v132 offset:32
	ds_write_b16_d16_hi v208, v132 offset:112
	ds_write_b16 v208, v133 offset:192
	ds_write_b16_d16_hi v208, v133 offset:272
	v_pk_mul_f32 v[128:129], v[96:97], v[190:191] op_sel_hi:[1,0]
	v_pk_mul_f32 v[130:131], v[98:99], v[190:191] op_sel_hi:[1,0]
	v_add_u32_e32 v244, 0x8000, v220
	global_store_dwordx4 v244, v[128:131], s[48:49] offset:576 sc1
	v_cvt_pk_bf16_f32 v132, v128, v129
	v_cvt_pk_bf16_f32 v133, v130, v131
	ds_write_b16 v208, v132 offset:1312
	ds_write_b16_d16_hi v208, v132 offset:1392
	ds_write_b16 v208, v133 offset:1472
	ds_write_b16_d16_hi v208, v133 offset:1552
	s_waitcnt lgkmcnt(0)
	ds_read_b128 v[212:215], v209
	ds_read_b128 v[216:219], v209 offset:1280
	s_add_u32 s46, s44, s101
	s_addc_u32 s47, s45, 0
	s_add_u32 s46, s46, s100
	s_addc_u32 s47, s47, 0
	s_waitcnt lgkmcnt(0)
	global_store_dwordx4 v210, v[212:215], s[46:47]
	global_store_dwordx4 v211, v[216:219], s[46:47]
	v_pk_mul_f32 v[128:129], v[84:85], v[172:173] op_sel_hi:[1,0]
	v_pk_mul_f32 v[130:131], v[86:87], v[172:173] op_sel_hi:[1,0]
	v_add_u32_e32 v244, 0x10000, v220
	global_store_dwordx4 v244, v[128:131], s[48:49] offset:512 sc1
	v_cvt_pk_bf16_f32 v132, v128, v129
	v_cvt_pk_bf16_f32 v133, v130, v131
	ds_write_b16 v208, v132
	ds_write_b16_d16_hi v208, v132 offset:80
	ds_write_b16 v208, v133 offset:160
	ds_write_b16_d16_hi v208, v133 offset:240
	v_pk_mul_f32 v[128:129], v[80:81], v[172:173] op_sel_hi:[1,0]
	v_pk_mul_f32 v[130:131], v[82:83], v[172:173] op_sel_hi:[1,0]
	v_add_u32_e32 v244, 0x10000, v220
	global_store_dwordx4 v244, v[128:131], s[48:49] offset:576 sc1
	v_cvt_pk_bf16_f32 v132, v128, v129
	v_cvt_pk_bf16_f32 v133, v130, v131
	ds_write_b16 v208, v132 offset:1280
	ds_write_b16_d16_hi v208, v132 offset:1360
	ds_write_b16 v208, v133 offset:1440
	ds_write_b16_d16_hi v208, v133 offset:1520
	v_pk_mul_f32 v[128:129], v[68:69], v[168:169] op_sel_hi:[1,0]
	v_pk_mul_f32 v[130:131], v[70:71], v[168:169] op_sel_hi:[1,0]
	v_add_u32_e32 v244, 0x18000, v220
	global_store_dwordx4 v244, v[128:131], s[48:49] offset:512 sc1
	v_cvt_pk_bf16_f32 v132, v128, v129
	v_cvt_pk_bf16_f32 v133, v130, v131
	ds_write_b16 v208, v132 offset:32
	ds_write_b16_d16_hi v208, v132 offset:112
	ds_write_b16 v208, v133 offset:192
	ds_write_b16_d16_hi v208, v133 offset:272
	v_pk_mul_f32 v[128:129], v[64:65], v[168:169] op_sel_hi:[1,0]
	v_pk_mul_f32 v[130:131], v[66:67], v[168:169] op_sel_hi:[1,0]
	v_add_u32_e32 v244, 0x18000, v220
	global_store_dwordx4 v244, v[128:131], s[48:49] offset:576 sc1
	v_cvt_pk_bf16_f32 v132, v128, v129
	v_cvt_pk_bf16_f32 v133, v130, v131
	ds_write_b16 v208, v132 offset:1312
	ds_write_b16_d16_hi v208, v132 offset:1392
	ds_write_b16 v208, v133 offset:1472
	ds_write_b16_d16_hi v208, v133 offset:1552
	s_waitcnt lgkmcnt(0)
	ds_read_b128 v[212:215], v209
	ds_read_b128 v[216:219], v209 offset:1280
	s_add_u32 s46, s44, s101
	s_addc_u32 s47, s45, 0
	s_add_u32 s46, s46, s100
	s_addc_u32 s47, s47, 0
	s_waitcnt lgkmcnt(0)
	global_store_dwordx4 v210, v[212:215], s[46:47] offset:64
	global_store_dwordx4 v211, v[216:219], s[46:47] offset:64
	v_pk_mul_f32 v[128:129], v[60:61], v[164:165] op_sel_hi:[1,0]
	v_pk_mul_f32 v[130:131], v[62:63], v[164:165] op_sel_hi:[1,0]
	v_add_u32_e32 v244, 0x40000, v220
	global_store_dwordx4 v244, v[128:131], s[48:49] sc1
	v_cvt_pk_bf16_f32 v132, v128, v129
	v_cvt_pk_bf16_f32 v133, v130, v131
	ds_write_b16 v208, v132
	ds_write_b16_d16_hi v208, v132 offset:80
	ds_write_b16 v208, v133 offset:160
	ds_write_b16_d16_hi v208, v133 offset:240
	v_pk_mul_f32 v[128:129], v[56:57], v[164:165] op_sel_hi:[1,0]
	v_pk_mul_f32 v[130:131], v[58:59], v[164:165] op_sel_hi:[1,0]
	v_add_u32_e32 v244, 0x40000, v220
	global_store_dwordx4 v244, v[128:131], s[48:49] offset:64 sc1
	v_cvt_pk_bf16_f32 v132, v128, v129
	v_cvt_pk_bf16_f32 v133, v130, v131
	ds_write_b16 v208, v132 offset:1280
	ds_write_b16_d16_hi v208, v132 offset:1360
	ds_write_b16 v208, v133 offset:1440
	ds_write_b16_d16_hi v208, v133 offset:1520
	v_pk_mul_f32 v[128:129], v[44:45], v[160:161] op_sel_hi:[1,0]
	v_pk_mul_f32 v[130:131], v[46:47], v[160:161] op_sel_hi:[1,0]
	v_add_u32_e32 v244, 0x48000, v220
	global_store_dwordx4 v244, v[128:131], s[48:49] sc1
	v_cvt_pk_bf16_f32 v132, v128, v129
	v_cvt_pk_bf16_f32 v133, v130, v131
	ds_write_b16 v208, v132 offset:32
	ds_write_b16_d16_hi v208, v132 offset:112
	ds_write_b16 v208, v133 offset:192
	ds_write_b16_d16_hi v208, v133 offset:272
	v_pk_mul_f32 v[128:129], v[40:41], v[160:161] op_sel_hi:[1,0]
	v_pk_mul_f32 v[130:131], v[42:43], v[160:161] op_sel_hi:[1,0]
	v_add_u32_e32 v244, 0x48000, v220
	global_store_dwordx4 v244, v[128:131], s[48:49] offset:64 sc1
	v_cvt_pk_bf16_f32 v132, v128, v129
	v_cvt_pk_bf16_f32 v133, v130, v131
	ds_write_b16 v208, v132 offset:1312
	ds_write_b16_d16_hi v208, v132 offset:1392
	ds_write_b16 v208, v133 offset:1472
	ds_write_b16_d16_hi v208, v133 offset:1552
	s_waitcnt lgkmcnt(0)
	ds_read_b128 v[212:215], v209
	ds_read_b128 v[216:219], v209 offset:1280
	s_add_u32 s46, s44, s38
	s_addc_u32 s47, s45, 0
	s_waitcnt lgkmcnt(0)
	global_store_dwordx4 v210, v[212:215], s[46:47]
	global_store_dwordx4 v211, v[216:219], s[46:47]
	v_pk_mul_f32 v[128:129], v[28:29], v[156:157] op_sel_hi:[1,0]
	v_pk_mul_f32 v[130:131], v[30:31], v[156:157] op_sel_hi:[1,0]
	v_add_u32_e32 v244, 0x50000, v220
	global_store_dwordx4 v244, v[128:131], s[48:49] sc1
	v_cvt_pk_bf16_f32 v132, v128, v129
	v_cvt_pk_bf16_f32 v133, v130, v131
	ds_write_b16 v208, v132
	ds_write_b16_d16_hi v208, v132 offset:80
	ds_write_b16 v208, v133 offset:160
	ds_write_b16_d16_hi v208, v133 offset:240
	v_pk_mul_f32 v[128:129], v[24:25], v[156:157] op_sel_hi:[1,0]
	v_pk_mul_f32 v[130:131], v[26:27], v[156:157] op_sel_hi:[1,0]
	v_add_u32_e32 v244, 0x50000, v220
	global_store_dwordx4 v244, v[128:131], s[48:49] offset:64 sc1
	v_cvt_pk_bf16_f32 v132, v128, v129
	v_cvt_pk_bf16_f32 v133, v130, v131
	ds_write_b16 v208, v132 offset:1280
	ds_write_b16_d16_hi v208, v132 offset:1360
	ds_write_b16 v208, v133 offset:1440
	ds_write_b16_d16_hi v208, v133 offset:1520
	v_pk_mul_f32 v[128:129], v[12:13], v[152:153] op_sel_hi:[1,0]
	v_pk_mul_f32 v[130:131], v[14:15], v[152:153] op_sel_hi:[1,0]
	v_add_u32_e32 v244, 0x58000, v220
	global_store_dwordx4 v244, v[128:131], s[48:49] sc1
	v_cvt_pk_bf16_f32 v132, v128, v129
	v_cvt_pk_bf16_f32 v133, v130, v131
	ds_write_b16 v208, v132 offset:32
	ds_write_b16_d16_hi v208, v132 offset:112
	ds_write_b16 v208, v133 offset:192
	ds_write_b16_d16_hi v208, v133 offset:272
	v_pk_mul_f32 v[128:129], v[8:9], v[152:153] op_sel_hi:[1,0]
	v_pk_mul_f32 v[130:131], v[10:11], v[152:153] op_sel_hi:[1,0]
	v_add_u32_e32 v244, 0x58000, v220
	global_store_dwordx4 v244, v[128:131], s[48:49] offset:64 sc1
	v_cvt_pk_bf16_f32 v132, v128, v129
	v_cvt_pk_bf16_f32 v133, v130, v131
	ds_write_b16 v208, v132 offset:1312
	ds_write_b16_d16_hi v208, v132 offset:1392
	ds_write_b16 v208, v133 offset:1472
	ds_write_b16_d16_hi v208, v133 offset:1552
	s_waitcnt lgkmcnt(0)
	ds_read_b128 v[212:215], v209
	ds_read_b128 v[216:219], v209 offset:1280
	s_add_u32 s46, s44, s38
	s_addc_u32 s47, s45, 0
	s_waitcnt lgkmcnt(0)
	global_store_dwordx4 v210, v[212:215], s[46:47] offset:64
	global_store_dwordx4 v211, v[216:219], s[46:47] offset:64
	v_pk_mul_f32 v[128:129], v[52:53], v[164:165] op_sel_hi:[1,0]
	v_pk_mul_f32 v[130:131], v[54:55], v[164:165] op_sel_hi:[1,0]
	v_add_u32_e32 v244, 0x40000, v220
	global_store_dwordx4 v244, v[128:131], s[48:49] offset:512 sc1
	v_cvt_pk_bf16_f32 v132, v128, v129
	v_cvt_pk_bf16_f32 v133, v130, v131
	ds_write_b16 v208, v132
	ds_write_b16_d16_hi v208, v132 offset:80
	ds_write_b16 v208, v133 offset:160
	ds_write_b16_d16_hi v208, v133 offset:240
	v_pk_mul_f32 v[128:129], v[48:49], v[164:165] op_sel_hi:[1,0]
	v_pk_mul_f32 v[130:131], v[50:51], v[164:165] op_sel_hi:[1,0]
	v_add_u32_e32 v244, 0x40000, v220
	global_store_dwordx4 v244, v[128:131], s[48:49] offset:576 sc1
	v_cvt_pk_bf16_f32 v132, v128, v129
	v_cvt_pk_bf16_f32 v133, v130, v131
	ds_write_b16 v208, v132 offset:1280
	ds_write_b16_d16_hi v208, v132 offset:1360
	ds_write_b16 v208, v133 offset:1440
	ds_write_b16_d16_hi v208, v133 offset:1520
	v_pk_mul_f32 v[128:129], v[36:37], v[160:161] op_sel_hi:[1,0]
	v_pk_mul_f32 v[130:131], v[38:39], v[160:161] op_sel_hi:[1,0]
	v_add_u32_e32 v244, 0x48000, v220
	global_store_dwordx4 v244, v[128:131], s[48:49] offset:512 sc1
	v_cvt_pk_bf16_f32 v132, v128, v129
	v_cvt_pk_bf16_f32 v133, v130, v131
	ds_write_b16 v208, v132 offset:32
	ds_write_b16_d16_hi v208, v132 offset:112
	ds_write_b16 v208, v133 offset:192
	ds_write_b16_d16_hi v208, v133 offset:272
	v_pk_mul_f32 v[128:129], v[32:33], v[160:161] op_sel_hi:[1,0]
	v_pk_mul_f32 v[130:131], v[34:35], v[160:161] op_sel_hi:[1,0]
	v_add_u32_e32 v244, 0x48000, v220
	global_store_dwordx4 v244, v[128:131], s[48:49] offset:576 sc1
	v_cvt_pk_bf16_f32 v132, v128, v129
	v_cvt_pk_bf16_f32 v133, v130, v131
	ds_write_b16 v208, v132 offset:1312
	ds_write_b16_d16_hi v208, v132 offset:1392
	ds_write_b16 v208, v133 offset:1472
	ds_write_b16_d16_hi v208, v133 offset:1552
	s_waitcnt lgkmcnt(0)
	ds_read_b128 v[212:215], v209
	ds_read_b128 v[216:219], v209 offset:1280
	s_add_u32 s46, s44, s38
	s_addc_u32 s47, s45, 0
	s_add_u32 s46, s46, s100
	s_addc_u32 s47, s47, 0
	s_waitcnt lgkmcnt(0)
	global_store_dwordx4 v210, v[212:215], s[46:47]
	global_store_dwordx4 v211, v[216:219], s[46:47]
	v_pk_mul_f32 v[128:129], v[20:21], v[156:157] op_sel_hi:[1,0]
	v_pk_mul_f32 v[130:131], v[22:23], v[156:157] op_sel_hi:[1,0]
	v_add_u32_e32 v244, 0x50000, v220
	global_store_dwordx4 v244, v[128:131], s[48:49] offset:512 sc1
	v_cvt_pk_bf16_f32 v132, v128, v129
	v_cvt_pk_bf16_f32 v133, v130, v131
	ds_write_b16 v208, v132
	ds_write_b16_d16_hi v208, v132 offset:80
	ds_write_b16 v208, v133 offset:160
	ds_write_b16_d16_hi v208, v133 offset:240
	v_pk_mul_f32 v[128:129], v[16:17], v[156:157] op_sel_hi:[1,0]
	v_pk_mul_f32 v[130:131], v[18:19], v[156:157] op_sel_hi:[1,0]
	v_add_u32_e32 v244, 0x50000, v220
	global_store_dwordx4 v244, v[128:131], s[48:49] offset:576 sc1
	v_cvt_pk_bf16_f32 v132, v128, v129
	v_cvt_pk_bf16_f32 v133, v130, v131
	ds_write_b16 v208, v132 offset:1280
	ds_write_b16_d16_hi v208, v132 offset:1360
	ds_write_b16 v208, v133 offset:1440
	ds_write_b16_d16_hi v208, v133 offset:1520
	v_pk_mul_f32 v[128:129], v[4:5], v[152:153] op_sel_hi:[1,0]
	v_pk_mul_f32 v[130:131], v[6:7], v[152:153] op_sel_hi:[1,0]
	v_add_u32_e32 v244, 0x58000, v220
	global_store_dwordx4 v244, v[128:131], s[48:49] offset:512 sc1
	v_cvt_pk_bf16_f32 v132, v128, v129
	v_cvt_pk_bf16_f32 v133, v130, v131
	ds_write_b16 v208, v132 offset:32
	ds_write_b16_d16_hi v208, v132 offset:112
	ds_write_b16 v208, v133 offset:192
	ds_write_b16_d16_hi v208, v133 offset:272
	v_pk_mul_f32 v[128:129], v[0:1], v[152:153] op_sel_hi:[1,0]
	v_pk_mul_f32 v[130:131], v[2:3], v[152:153] op_sel_hi:[1,0]
	v_add_u32_e32 v244, 0x58000, v220
	global_store_dwordx4 v244, v[128:131], s[48:49] offset:576 sc1
	v_cvt_pk_bf16_f32 v132, v128, v129
	v_cvt_pk_bf16_f32 v133, v130, v131
	ds_write_b16 v208, v132 offset:1312
	ds_write_b16_d16_hi v208, v132 offset:1392
	ds_write_b16 v208, v133 offset:1472
	ds_write_b16_d16_hi v208, v133 offset:1552
	s_waitcnt lgkmcnt(0)
	ds_read_b128 v[212:215], v209
	ds_read_b128 v[216:219], v209 offset:1280
	s_add_u32 s46, s44, s38
	s_addc_u32 s47, s45, 0
	s_add_u32 s46, s46, s100
	s_addc_u32 s47, s47, 0
	s_waitcnt lgkmcnt(0)
	global_store_dwordx4 v210, v[212:215], s[46:47] offset:64
	global_store_dwordx4 v211, v[216:219], s[46:47] offset:64
	s_branch .LBB0_586

.LresJ_yout:
	v_mov_b32_e32 v238, v151
	global_load_dwordx2 v[192:193], v238, s[96:97]
	global_load_dwordx2 v[194:195], v238, s[96:97] offset:32
	global_load_dwordx2 v[196:197], v238, s[96:97] offset:256
	global_load_dwordx2 v[198:199], v238, s[96:97] offset:288
	v_add_u32_e32 v238, 0x8000, v238
	global_load_dwordx2 v[200:201], v238, s[96:97]
	global_load_dwordx2 v[202:203], v238, s[96:97] offset:32
	global_load_dwordx2 v[204:205], v238, s[96:97] offset:256
	global_load_dwordx2 v[206:207], v238, s[96:97] offset:288
	v_add_u32_e32 v238, 0x8000, v238
	global_load_dwordx2 v[208:209], v238, s[96:97]
	global_load_dwordx2 v[210:211], v238, s[96:97] offset:32
	global_load_dwordx2 v[212:213], v238, s[96:97] offset:256
	global_load_dwordx2 v[214:215], v238, s[96:97] offset:288
	v_add_u32_e32 v238, 0x8000, v238
	global_load_dwordx2 v[216:217], v238, s[96:97]
	global_load_dwordx2 v[218:219], v238, s[96:97] offset:32
	global_load_dwordx2 v[220:221], v238, s[96:97] offset:256
	global_load_dwordx2 v[222:223], v238, s[96:97] offset:288
	v_add_u32_e32 v238, 0x28000, v238
	global_load_dwordx2 v[128:129], v238, s[96:97]
	global_load_dwordx2 v[130:131], v238, s[96:97] offset:32
	global_load_dwordx2 v[132:133], v238, s[96:97] offset:256
	global_load_dwordx2 v[134:135], v238, s[96:97] offset:288
	v_add_u32_e32 v238, 0x8000, v238
	global_load_dwordx2 v[136:137], v238, s[96:97]
	global_load_dwordx2 v[138:139], v238, s[96:97] offset:32
	global_load_dwordx2 v[140:141], v238, s[96:97] offset:256
	global_load_dwordx2 v[142:143], v238, s[96:97] offset:288
	v_add_u32_e32 v238, 0x8000, v238
	global_load_dwordx2 v[164:165], v238, s[96:97]
	global_load_dwordx2 v[166:167], v238, s[96:97] offset:32
	global_load_dwordx2 v[168:169], v238, s[96:97] offset:256
	global_load_dwordx2 v[170:171], v238, s[96:97] offset:288
	v_add_u32_e32 v238, 0x8000, v238
	global_load_dwordx2 v[172:173], v238, s[96:97]
	global_load_dwordx2 v[174:175], v238, s[96:97] offset:32
	global_load_dwordx2 v[240:241], v238, s[96:97] offset:256
	global_load_dwordx2 v[242:243], v238, s[96:97] offset:288
	s_waitcnt vmcnt(31)
	v_lshlrev_b32_e32 v252, 16, v192
	v_and_b32_e32 v253, 0xffff0000, v192
	v_lshlrev_b32_e32 v254, 16, v193
	v_and_b32_e32 v255, 0xffff0000, v193
	v_pk_add_f32 v[252:253], v[124:125], v[252:253]
	v_pk_add_f32 v[254:255], v[126:127], v[254:255]
	v_mul_f32_e32 v154, v252, v252
	v_fmac_f32_e32 v154, v253, v253
	v_fmac_f32_e32 v154, v254, v254
	v_fmac_f32_e32 v154, v255, v255
	global_store_dwordx4 v150, v[252:255], s[26:27] sc1
	s_nop 1
	s_waitcnt vmcnt(31)
	v_lshlrev_b32_e32 v252, 16, v194
	v_and_b32_e32 v253, 0xffff0000, v194
	v_lshlrev_b32_e32 v254, 16, v195
	v_and_b32_e32 v255, 0xffff0000, v195
	v_pk_add_f32 v[252:253], v[120:121], v[252:253]
	v_pk_add_f32 v[254:255], v[122:123], v[254:255]
	v_fmac_f32_e32 v154, v252, v252
	v_fmac_f32_e32 v154, v253, v253
	v_fmac_f32_e32 v154, v254, v254
	v_fmac_f32_e32 v154, v255, v255
	global_store_dwordx4 v150, v[252:255], s[26:27] offset:64 sc1
	s_nop 1
	s_waitcnt vmcnt(31)
	v_lshlrev_b32_e32 v252, 16, v196
	v_and_b32_e32 v253, 0xffff0000, v196
	v_lshlrev_b32_e32 v254, 16, v197
	v_and_b32_e32 v255, 0xffff0000, v197
	v_pk_add_f32 v[252:253], v[108:109], v[252:253]
	v_pk_add_f32 v[254:255], v[110:111], v[254:255]
	v_fmac_f32_e32 v154, v252, v252
	v_fmac_f32_e32 v154, v253, v253
	v_fmac_f32_e32 v154, v254, v254
	v_fmac_f32_e32 v154, v255, v255
	global_store_dwordx4 v150, v[252:255], s[26:27] offset:512 sc1
	s_nop 1
	s_waitcnt vmcnt(31)
	v_lshlrev_b32_e32 v252, 16, v198
	v_and_b32_e32 v253, 0xffff0000, v198
	v_lshlrev_b32_e32 v254, 16, v199
	v_and_b32_e32 v255, 0xffff0000, v199
	v_pk_add_f32 v[252:253], v[100:101], v[252:253]
	v_pk_add_f32 v[254:255], v[102:103], v[254:255]
	v_fmac_f32_e32 v154, v252, v252
	v_fmac_f32_e32 v154, v253, v253
	v_fmac_f32_e32 v154, v254, v254
	v_fmac_f32_e32 v154, v255, v255
	global_store_dwordx4 v150, v[252:255], s[26:27] offset:576 sc1
	s_nop 1
	v_add_u32_e32 v150, 0x10000, v150
	s_waitcnt vmcnt(31)
	v_lshlrev_b32_e32 v252, 16, v200
	v_and_b32_e32 v253, 0xffff0000, v200
	v_lshlrev_b32_e32 v254, 16, v201
	v_and_b32_e32 v255, 0xffff0000, v201
	v_pk_add_f32 v[252:253], v[116:117], v[252:253]
	v_pk_add_f32 v[254:255], v[118:119], v[254:255]
	v_mul_f32_e32 v155, v252, v252
	v_fmac_f32_e32 v155, v253, v253
	v_fmac_f32_e32 v155, v254, v254
	v_fmac_f32_e32 v155, v255, v255
	global_store_dwordx4 v150, v[252:255], s[26:27] sc1
	s_nop 1
	s_waitcnt vmcnt(31)
	v_lshlrev_b32_e32 v252, 16, v202
	v_and_b32_e32 v253, 0xffff0000, v202
	v_lshlrev_b32_e32 v254, 16, v203
	v_and_b32_e32 v255, 0xffff0000, v203
	v_pk_add_f32 v[252:253], v[112:113], v[252:253]
	v_pk_add_f32 v[254:255], v[114:115], v[254:255]
	v_fmac_f32_e32 v155, v252, v252
	v_fmac_f32_e32 v155, v253, v253
	v_fmac_f32_e32 v155, v254, v254
	v_fmac_f32_e32 v155, v255, v255
	global_store_dwordx4 v150, v[252:255], s[26:27] offset:64 sc1
	s_nop 1
	s_waitcnt vmcnt(31)
	v_lshlrev_b32_e32 v252, 16, v204
	v_and_b32_e32 v253, 0xffff0000, v204
	v_lshlrev_b32_e32 v254, 16, v205
	v_and_b32_e32 v255, 0xffff0000, v205
	v_pk_add_f32 v[252:253], v[92:93], v[252:253]
	v_pk_add_f32 v[254:255], v[94:95], v[254:255]
	v_fmac_f32_e32 v155, v252, v252
	v_fmac_f32_e32 v155, v253, v253
	v_fmac_f32_e32 v155, v254, v254
	v_fmac_f32_e32 v155, v255, v255
	global_store_dwordx4 v150, v[252:255], s[26:27] offset:512 sc1
	s_nop 1
	s_waitcnt vmcnt(31)
	v_lshlrev_b32_e32 v252, 16, v206
	v_and_b32_e32 v253, 0xffff0000, v206
	v_lshlrev_b32_e32 v254, 16, v207
	v_and_b32_e32 v255, 0xffff0000, v207
	v_pk_add_f32 v[252:253], v[84:85], v[252:253]
	v_pk_add_f32 v[254:255], v[86:87], v[254:255]
	v_fmac_f32_e32 v155, v252, v252
	v_fmac_f32_e32 v155, v253, v253
	v_fmac_f32_e32 v155, v254, v254
	v_fmac_f32_e32 v155, v255, v255
	global_store_dwordx4 v150, v[252:255], s[26:27] offset:576 sc1
	s_nop 1
	v_add_u32_e32 v150, 0x10000, v150
	s_waitcnt vmcnt(31)
	v_lshlrev_b32_e32 v252, 16, v208
	v_and_b32_e32 v253, 0xffff0000, v208
	v_lshlrev_b32_e32 v254, 16, v209
	v_and_b32_e32 v255, 0xffff0000, v209
	v_pk_add_f32 v[252:253], v[104:105], v[252:253]
	v_pk_add_f32 v[254:255], v[106:107], v[254:255]
	v_mul_f32_e32 v156, v252, v252
	v_fmac_f32_e32 v156, v253, v253
	v_fmac_f32_e32 v156, v254, v254
	v_fmac_f32_e32 v156, v255, v255
	global_store_dwordx4 v150, v[252:255], s[26:27] sc1
	s_nop 1
	s_waitcnt vmcnt(31)
	v_lshlrev_b32_e32 v252, 16, v210
	v_and_b32_e32 v253, 0xffff0000, v210
	v_lshlrev_b32_e32 v254, 16, v211
	v_and_b32_e32 v255, 0xffff0000, v211
	v_pk_add_f32 v[252:253], v[96:97], v[252:253]
	v_pk_add_f32 v[254:255], v[98:99], v[254:255]
	v_fmac_f32_e32 v156, v252, v252
	v_fmac_f32_e32 v156, v253, v253
	v_fmac_f32_e32 v156, v254, v254
	v_fmac_f32_e32 v156, v255, v255
	global_store_dwordx4 v150, v[252:255], s[26:27] offset:64 sc1
	s_nop 1
	s_waitcnt vmcnt(31)
	v_lshlrev_b32_e32 v252, 16, v212
	v_and_b32_e32 v253, 0xffff0000, v212
	v_lshlrev_b32_e32 v254, 16, v213
	v_and_b32_e32 v255, 0xffff0000, v213
	v_pk_add_f32 v[252:253], v[76:77], v[252:253]
	v_pk_add_f32 v[254:255], v[78:79], v[254:255]
	v_fmac_f32_e32 v156, v252, v252
	v_fmac_f32_e32 v156, v253, v253
	v_fmac_f32_e32 v156, v254, v254
	v_fmac_f32_e32 v156, v255, v255
	global_store_dwordx4 v150, v[252:255], s[26:27] offset:512 sc1
	s_nop 1
	s_waitcnt vmcnt(31)
	v_lshlrev_b32_e32 v252, 16, v214
	v_and_b32_e32 v253, 0xffff0000, v214
	v_lshlrev_b32_e32 v254, 16, v215
	v_and_b32_e32 v255, 0xffff0000, v215
	v_pk_add_f32 v[252:253], v[72:73], v[252:253]
	v_pk_add_f32 v[254:255], v[74:75], v[254:255]
	v_fmac_f32_e32 v156, v252, v252
	v_fmac_f32_e32 v156, v253, v253
	v_fmac_f32_e32 v156, v254, v254
	v_fmac_f32_e32 v156, v255, v255
	global_store_dwordx4 v150, v[252:255], s[26:27] offset:576 sc1
	s_nop 1
	v_add_u32_e32 v150, 0x10000, v150
	s_waitcnt vmcnt(31)
	v_lshlrev_b32_e32 v252, 16, v216
	v_and_b32_e32 v253, 0xffff0000, v216
	v_lshlrev_b32_e32 v254, 16, v217
	v_and_b32_e32 v255, 0xffff0000, v217
	v_pk_add_f32 v[252:253], v[88:89], v[252:253]
	v_pk_add_f32 v[254:255], v[90:91], v[254:255]
	v_mul_f32_e32 v157, v252, v252
	v_fmac_f32_e32 v157, v253, v253
	v_fmac_f32_e32 v157, v254, v254
	v_fmac_f32_e32 v157, v255, v255
	global_store_dwordx4 v150, v[252:255], s[26:27] sc1
	s_nop 1
	s_waitcnt vmcnt(31)
	v_lshlrev_b32_e32 v252, 16, v218
	v_and_b32_e32 v253, 0xffff0000, v218
	v_lshlrev_b32_e32 v254, 16, v219
	v_and_b32_e32 v255, 0xffff0000, v219
	v_pk_add_f32 v[252:253], v[80:81], v[252:253]
	v_pk_add_f32 v[254:255], v[82:83], v[254:255]
	v_fmac_f32_e32 v157, v252, v252
	v_fmac_f32_e32 v157, v253, v253
	v_fmac_f32_e32 v157, v254, v254
	v_fmac_f32_e32 v157, v255, v255
	global_store_dwordx4 v150, v[252:255], s[26:27] offset:64 sc1
	s_nop 1
	s_waitcnt vmcnt(31)
	v_lshlrev_b32_e32 v252, 16, v220
	v_and_b32_e32 v253, 0xffff0000, v220
	v_lshlrev_b32_e32 v254, 16, v221
	v_and_b32_e32 v255, 0xffff0000, v221
	v_pk_add_f32 v[252:253], v[68:69], v[252:253]
	v_pk_add_f32 v[254:255], v[70:71], v[254:255]
	v_fmac_f32_e32 v157, v252, v252
	v_fmac_f32_e32 v157, v253, v253
	v_fmac_f32_e32 v157, v254, v254
	v_fmac_f32_e32 v157, v255, v255
	global_store_dwordx4 v150, v[252:255], s[26:27] offset:512 sc1
	s_nop 1
	s_waitcnt vmcnt(31)
	v_lshlrev_b32_e32 v252, 16, v222
	v_and_b32_e32 v253, 0xffff0000, v222
	v_lshlrev_b32_e32 v254, 16, v223
	v_and_b32_e32 v255, 0xffff0000, v223
	v_pk_add_f32 v[252:253], v[64:65], v[252:253]
	v_pk_add_f32 v[254:255], v[66:67], v[254:255]
	v_fmac_f32_e32 v157, v252, v252
	v_fmac_f32_e32 v157, v253, v253
	v_fmac_f32_e32 v157, v254, v254
	v_fmac_f32_e32 v157, v255, v255
	global_store_dwordx4 v150, v[252:255], s[26:27] offset:576 sc1
	s_nop 1
	v_add_u32_e32 v150, 0x50000, v150
	s_waitcnt vmcnt(31)
	v_lshlrev_b32_e32 v252, 16, v128
	v_and_b32_e32 v253, 0xffff0000, v128
	v_lshlrev_b32_e32 v254, 16, v129
	v_and_b32_e32 v255, 0xffff0000, v129
	v_pk_add_f32 v[252:253], v[60:61], v[252:253]
	v_pk_add_f32 v[254:255], v[62:63], v[254:255]
	v_mul_f32_e32 v244, v252, v252
	v_fmac_f32_e32 v244, v253, v253
	v_fmac_f32_e32 v244, v254, v254
	v_fmac_f32_e32 v244, v255, v255
	global_store_dwordx4 v150, v[252:255], s[26:27] sc1
	s_nop 1
	s_waitcnt vmcnt(31)
	v_lshlrev_b32_e32 v252, 16, v130
	v_and_b32_e32 v253, 0xffff0000, v130
	v_lshlrev_b32_e32 v254, 16, v131
	v_and_b32_e32 v255, 0xffff0000, v131
	v_pk_add_f32 v[252:253], v[56:57], v[252:253]
	v_pk_add_f32 v[254:255], v[58:59], v[254:255]
	v_fmac_f32_e32 v244, v252, v252
	v_fmac_f32_e32 v244, v253, v253
	v_fmac_f32_e32 v244, v254, v254
	v_fmac_f32_e32 v244, v255, v255
	global_store_dwordx4 v150, v[252:255], s[26:27] offset:64 sc1
	s_nop 1
	s_waitcnt vmcnt(31)
	v_lshlrev_b32_e32 v252, 16, v132
	v_and_b32_e32 v253, 0xffff0000, v132
	v_lshlrev_b32_e32 v254, 16, v133
	v_and_b32_e32 v255, 0xffff0000, v133
	v_pk_add_f32 v[252:253], v[44:45], v[252:253]
	v_pk_add_f32 v[254:255], v[46:47], v[254:255]
	v_fmac_f32_e32 v244, v252, v252
	v_fmac_f32_e32 v244, v253, v253
	v_fmac_f32_e32 v244, v254, v254
	v_fmac_f32_e32 v244, v255, v255
	global_store_dwordx4 v150, v[252:255], s[26:27] offset:512 sc1
	s_nop 1
	s_waitcnt vmcnt(31)
	v_lshlrev_b32_e32 v252, 16, v134
	v_and_b32_e32 v253, 0xffff0000, v134
	v_lshlrev_b32_e32 v254, 16, v135
	v_and_b32_e32 v255, 0xffff0000, v135
	v_pk_add_f32 v[252:253], v[36:37], v[252:253]
	v_pk_add_f32 v[254:255], v[38:39], v[254:255]
	v_fmac_f32_e32 v244, v252, v252
	v_fmac_f32_e32 v244, v253, v253
	v_fmac_f32_e32 v244, v254, v254
	v_fmac_f32_e32 v244, v255, v255
	global_store_dwordx4 v150, v[252:255], s[26:27] offset:576 sc1
	s_nop 1
	v_add_u32_e32 v150, 0x10000, v150
	s_waitcnt vmcnt(31)
	v_lshlrev_b32_e32 v252, 16, v136
	v_and_b32_e32 v253, 0xffff0000, v136
	v_lshlrev_b32_e32 v254, 16, v137
	v_and_b32_e32 v255, 0xffff0000, v137
	v_pk_add_f32 v[252:253], v[52:53], v[252:253]
	v_pk_add_f32 v[254:255], v[54:55], v[254:255]
	v_mul_f32_e32 v245, v252, v252
	v_fmac_f32_e32 v245, v253, v253
	v_fmac_f32_e32 v245, v254, v254
	v_fmac_f32_e32 v245, v255, v255
	global_store_dwordx4 v150, v[252:255], s[26:27] sc1
	s_nop 1
	s_waitcnt vmcnt(31)
	v_lshlrev_b32_e32 v252, 16, v138
	v_and_b32_e32 v253, 0xffff0000, v138
	v_lshlrev_b32_e32 v254, 16, v139
	v_and_b32_e32 v255, 0xffff0000, v139
	v_pk_add_f32 v[252:253], v[48:49], v[252:253]
	v_pk_add_f32 v[254:255], v[50:51], v[254:255]
	v_fmac_f32_e32 v245, v252, v252
	v_fmac_f32_e32 v245, v253, v253
	v_fmac_f32_e32 v245, v254, v254
	v_fmac_f32_e32 v245, v255, v255
	global_store_dwordx4 v150, v[252:255], s[26:27] offset:64 sc1
	s_nop 1
	s_waitcnt vmcnt(31)
	v_lshlrev_b32_e32 v252, 16, v140
	v_and_b32_e32 v253, 0xffff0000, v140
	v_lshlrev_b32_e32 v254, 16, v141
	v_and_b32_e32 v255, 0xffff0000, v141
	v_pk_add_f32 v[252:253], v[28:29], v[252:253]
	v_pk_add_f32 v[254:255], v[30:31], v[254:255]
	v_fmac_f32_e32 v245, v252, v252
	v_fmac_f32_e32 v245, v253, v253
	v_fmac_f32_e32 v245, v254, v254
	v_fmac_f32_e32 v245, v255, v255
	global_store_dwordx4 v150, v[252:255], s[26:27] offset:512 sc1
	s_nop 1
	s_waitcnt vmcnt(31)
	v_lshlrev_b32_e32 v252, 16, v142
	v_and_b32_e32 v253, 0xffff0000, v142
	v_lshlrev_b32_e32 v254, 16, v143
	v_and_b32_e32 v255, 0xffff0000, v143
	v_pk_add_f32 v[252:253], v[20:21], v[252:253]
	v_pk_add_f32 v[254:255], v[22:23], v[254:255]
	v_fmac_f32_e32 v245, v252, v252
	v_fmac_f32_e32 v245, v253, v253
	v_fmac_f32_e32 v245, v254, v254
	v_fmac_f32_e32 v245, v255, v255
	global_store_dwordx4 v150, v[252:255], s[26:27] offset:576 sc1
	s_nop 1
	v_add_u32_e32 v150, 0x10000, v150
	s_waitcnt vmcnt(31)
	v_lshlrev_b32_e32 v252, 16, v164
	v_and_b32_e32 v253, 0xffff0000, v164
	v_lshlrev_b32_e32 v254, 16, v165
	v_and_b32_e32 v255, 0xffff0000, v165
	v_pk_add_f32 v[252:253], v[40:41], v[252:253]
	v_pk_add_f32 v[254:255], v[42:43], v[254:255]
	v_mul_f32_e32 v246, v252, v252
	v_fmac_f32_e32 v246, v253, v253
	v_fmac_f32_e32 v246, v254, v254
	v_fmac_f32_e32 v246, v255, v255
	global_store_dwordx4 v150, v[252:255], s[26:27] sc1
	s_nop 1
	s_waitcnt vmcnt(31)
	v_lshlrev_b32_e32 v252, 16, v166
	v_and_b32_e32 v253, 0xffff0000, v166
	v_lshlrev_b32_e32 v254, 16, v167
	v_and_b32_e32 v255, 0xffff0000, v167
	v_pk_add_f32 v[252:253], v[32:33], v[252:253]
	v_pk_add_f32 v[254:255], v[34:35], v[254:255]
	v_fmac_f32_e32 v246, v252, v252
	v_fmac_f32_e32 v246, v253, v253
	v_fmac_f32_e32 v246, v254, v254
	v_fmac_f32_e32 v246, v255, v255
	global_store_dwordx4 v150, v[252:255], s[26:27] offset:64 sc1
	s_nop 1
	s_waitcnt vmcnt(31)
	v_lshlrev_b32_e32 v252, 16, v168
	v_and_b32_e32 v253, 0xffff0000, v168
	v_lshlrev_b32_e32 v254, 16, v169
	v_and_b32_e32 v255, 0xffff0000, v169
	v_pk_add_f32 v[252:253], v[12:13], v[252:253]
	v_pk_add_f32 v[254:255], v[14:15], v[254:255]
	v_fmac_f32_e32 v246, v252, v252
	v_fmac_f32_e32 v246, v253, v253
	v_fmac_f32_e32 v246, v254, v254
	v_fmac_f32_e32 v246, v255, v255
	global_store_dwordx4 v150, v[252:255], s[26:27] offset:512 sc1
	s_nop 1
	s_waitcnt vmcnt(31)
	v_lshlrev_b32_e32 v252, 16, v170
	v_and_b32_e32 v253, 0xffff0000, v170
	v_lshlrev_b32_e32 v254, 16, v171
	v_and_b32_e32 v255, 0xffff0000, v171
	v_pk_add_f32 v[252:253], v[8:9], v[252:253]
	v_pk_add_f32 v[254:255], v[10:11], v[254:255]
	v_fmac_f32_e32 v246, v252, v252
	v_fmac_f32_e32 v246, v253, v253
	v_fmac_f32_e32 v246, v254, v254
	v_fmac_f32_e32 v246, v255, v255
	global_store_dwordx4 v150, v[252:255], s[26:27] offset:576 sc1
	s_nop 1
	v_add_u32_e32 v150, 0x10000, v150
	s_waitcnt vmcnt(31)
	v_lshlrev_b32_e32 v252, 16, v172
	v_and_b32_e32 v253, 0xffff0000, v172
	v_lshlrev_b32_e32 v254, 16, v173
	v_and_b32_e32 v255, 0xffff0000, v173
	v_pk_add_f32 v[252:253], v[24:25], v[252:253]
	v_pk_add_f32 v[254:255], v[26:27], v[254:255]
	v_mul_f32_e32 v247, v252, v252
	v_fmac_f32_e32 v247, v253, v253
	v_fmac_f32_e32 v247, v254, v254
	v_fmac_f32_e32 v247, v255, v255
	global_store_dwordx4 v150, v[252:255], s[26:27] sc1
	s_nop 1
	s_waitcnt vmcnt(31)
	v_lshlrev_b32_e32 v252, 16, v174
	v_and_b32_e32 v253, 0xffff0000, v174
	v_lshlrev_b32_e32 v254, 16, v175
	v_and_b32_e32 v255, 0xffff0000, v175
	v_pk_add_f32 v[252:253], v[16:17], v[252:253]
	v_pk_add_f32 v[254:255], v[18:19], v[254:255]
	v_fmac_f32_e32 v247, v252, v252
	v_fmac_f32_e32 v247, v253, v253
	v_fmac_f32_e32 v247, v254, v254
	v_fmac_f32_e32 v247, v255, v255
	global_store_dwordx4 v150, v[252:255], s[26:27] offset:64 sc1
	s_nop 1
	s_waitcnt vmcnt(31)
	v_lshlrev_b32_e32 v252, 16, v240
	v_and_b32_e32 v253, 0xffff0000, v240
	v_lshlrev_b32_e32 v254, 16, v241
	v_and_b32_e32 v255, 0xffff0000, v241
	v_pk_add_f32 v[252:253], v[4:5], v[252:253]
	v_pk_add_f32 v[254:255], v[6:7], v[254:255]
	v_fmac_f32_e32 v247, v252, v252
	v_fmac_f32_e32 v247, v253, v253
	v_fmac_f32_e32 v247, v254, v254
	v_fmac_f32_e32 v247, v255, v255
	global_store_dwordx4 v150, v[252:255], s[26:27] offset:512 sc1
	s_nop 1
	s_waitcnt vmcnt(31)
	v_lshlrev_b32_e32 v252, 16, v242
	v_and_b32_e32 v253, 0xffff0000, v242
	v_lshlrev_b32_e32 v254, 16, v243
	v_and_b32_e32 v255, 0xffff0000, v243
	v_pk_add_f32 v[252:253], v[0:1], v[252:253]
	v_pk_add_f32 v[254:255], v[2:3], v[254:255]
	v_fmac_f32_e32 v247, v252, v252
	v_fmac_f32_e32 v247, v253, v253
	v_fmac_f32_e32 v247, v254, v254
	v_fmac_f32_e32 v247, v255, v255
	global_store_dwordx4 v150, v[252:255], s[26:27] offset:576 sc1
	s_nop 1
	s_branch .LresJ_red
